# attention: K-tile LDS-DMA issued after the block barrier, closing wait vmcnt(1) (step toward half-block stagger of waves 4-7)
# baseline (speedup 1.0000x reference)
; #define WAIT_BAR(N) asm volatile("s_waitcnt vmcnt(" #N ") lgkmcnt(0)\n\ts_barrier":::"memory")
;   #define RESC() do{}while(0)
;   #define ROT() do{sl_prev=sl_cur;sl_cur=sl_next;sl_next=(sl_next==(NSLOT-1)*SLOTB)?0:sl_next+SLOTB;}while(0)
; template<int THRL> __device__ __forceinline__ void attn_unit(int b,int h,int qb,const bf16*Q,const bf16*__restrict__ K,const bf16*__restrict__ V,bf16*O,char*shm,float m2){
;     ...
;   int t=1;
;   for(;t+5<NT;t+=2){
;     STEP(pB0,pB1,pA0,pA1,t,true,true,true);     WAIT_BAR(2); RESC(); ROT();
.LBB0_829:
	v_add_u32_e32 v190, s17, v220
	ds_read_b64_tr_b16 v[230:231], v190 offset:24576
	ds_read_b64_tr_b16 v[232:233], v190 offset:25088
	s_waitcnt lgkmcnt(9)
	v_mfma_f32_32x32x16_bf16 v[114:129], v[98:101], v[174:177], v[50:65]
	v_exp_f32_e32 v78, v78
	v_add_f32_e32 v102, v82, v83
	v_add_f32_e32 v102, v84, v102
	v_add_f32_e32 v102, v85, v102
	v_add_f32_e32 v102, v86, v102
	v_add_f32_e32 v102, v87, v102
	v_cvt_pk_bf16_f32 v166, v82, v83
	v_cvt_pk_bf16_f32 v167, v84, v85
	ds_read_b64_tr_b16 v[82:83], v190 offset:28672
	ds_read_b64_tr_b16 v[84:85], v190 offset:29184
	v_add_f32_e32 v98, v88, v102
	v_add_f32_e32 v98, v89, v98
	v_add_f32_e32 v98, v90, v98
	v_add_f32_e32 v146, v91, v98
	s_waitcnt lgkmcnt(10)
	v_mfma_f32_32x32x16_bf16 v[98:113], v[182:185], v[174:177], v[50:65]
	v_exp_f32_e32 v79, v79
	v_cvt_pk_bf16_f32 v168, v86, v87
	v_cvt_pk_bf16_f32 v169, v88, v89
	ds_read_b64_tr_b16 v[86:87], v190 offset:25600
	ds_read_b64_tr_b16 v[88:89], v190 offset:26112
	v_add_f32_e32 v146, v92, v146
	v_add_f32_e32 v146, v93, v146
	v_add_f32_e32 v146, v94, v146
	v_add_f32_e32 v146, v95, v146
	v_cvt_pk_bf16_f32 v158, v90, v91
	v_cvt_pk_bf16_f32 v159, v92, v93
	s_waitcnt lgkmcnt(11)
	v_mfma_f32_32x32x16_bf16 v[114:129], v[186:189], v[170:173], v[114:129]
	v_exp_f32_e32 v80, v80
	ds_read_b64_tr_b16 v[90:91], v190 offset:29696
	ds_read_b64_tr_b16 v[92:93], v190 offset:30208
	s_waitcnt lgkmcnt(12)
	v_mfma_f32_32x32x16_bf16 v[98:113], v[178:181], v[170:173], v[98:113]
	v_exp_f32_e32 v81, v81
	v_add_f32_e32 v146, v96, v146
	v_add_f32_e32 v146, v97, v146
	v_add_f32_e32 v146, v66, v146
	v_add_f32_e32 v146, v67, v146
	v_cvt_pk_bf16_f32 v160, v94, v95
	v_cvt_pk_bf16_f32 v161, v96, v97
	ds_read_b64_tr_b16 v[94:95], v190 offset:26624
	ds_read_b64_tr_b16 v[96:97], v190 offset:27136
	s_waitcnt lgkmcnt(13)
	v_mfma_f32_32x32x16_bf16 v[114:129], v[142:145], v[162:165], v[114:129]
	v_add_f32_e32 v142, v68, v146
	v_add_f32_e32 v142, v69, v142
	v_add_f32_e32 v142, v70, v142
	v_add_f32_e32 v142, v71, v142
	v_cvt_pk_bf16_f32 v150, v66, v67
	v_cvt_pk_bf16_f32 v151, v68, v69
	ds_read_b64_tr_b16 v[66:67], v190 offset:30720
	ds_read_b64_tr_b16 v[68:69], v190 offset:31232
	s_waitcnt lgkmcnt(14)
	v_mfma_f32_32x32x16_bf16 v[98:113], v[138:141], v[162:165], v[98:113]
	v_add_f32_e32 v138, v72, v142
	v_add_f32_e32 v138, v73, v138
	v_add_f32_e32 v138, v74, v138
	v_add_f32_e32 v138, v75, v138
	v_cvt_pk_bf16_f32 v152, v70, v71
	v_cvt_pk_bf16_f32 v153, v72, v73
	ds_read_b64_tr_b16 v[70:71], v190 offset:27648
	ds_read_b64_tr_b16 v[72:73], v190 offset:28160
	s_waitcnt lgkmcnt(14)
	v_mfma_f32_32x32x16_bf16 v[114:129], v[134:137], v[154:157], v[114:129]
	v_add_f32_e32 v134, v76, v138
	v_add_f32_e32 v134, v77, v134
	v_add_f32_e32 v134, v78, v134
	v_add_f32_e32 v134, v79, v134
	v_cvt_pk_bf16_f32 v146, v74, v75
	v_cvt_pk_bf16_f32 v147, v76, v77
	ds_read_b64_tr_b16 v[74:75], v190 offset:31744
	ds_read_b64_tr_b16 v[76:77], v190 offset:32256
	v_mfma_f32_32x32x16_bf16 v[98:113], v[130:133], v[154:157], v[98:113]
	v_add_f32_e32 v130, v80, v134
	v_add_f32_e32 v130, v81, v130
	v_add_f32_e32 v130, 0, v130
	v_cvt_pk_bf16_f32 v148, v78, v79
	v_cvt_pk_bf16_f32 v149, v80, v81
	v_lshl_add_u64 v[78:79], v[216:217], 0, s[42:43]
	s_add_i32 s0, s15, s4
	s_mov_b32 s17, m0
	s_mov_b32 m0, s0
	s_nop 0
	global_load_lds_dwordx4 v[78:79], off
	s_mov_b32 m0, s17
	v_add_f32_e32 v190, v199, v130
	s_waitcnt lgkmcnt(14)
	v_mfma_f32_32x32x16_bf16 v[18:33], v[166:169], v[230:233], v[18:33]
	v_exp_f32_e32 v114, v114
	v_exp_f32_e32 v115, v115
	v_exp_f32_e32 v116, v116
	v_exp_f32_e32 v117, v117
	s_waitcnt lgkmcnt(12)
	v_mfma_f32_32x32x16_bf16 v[34:49], v[166:169], v[82:85], v[34:49]
	v_exp_f32_e32 v118, v118
	v_exp_f32_e32 v119, v119
	v_exp_f32_e32 v120, v120
	v_exp_f32_e32 v121, v121
	v_add_u32_e32 v82, s15, v219
	ds_read_b128 v[78:81], v82
	ds_read_b128 v[134:137], v82 offset:512
	s_waitcnt lgkmcnt(12)
	v_mfma_f32_32x32x16_bf16 v[18:33], v[158:161], v[86:89], v[18:33]
	v_exp_f32_e32 v122, v122
	v_exp_f32_e32 v123, v123
	v_exp_f32_e32 v124, v124
	v_exp_f32_e32 v125, v125
	ds_read_b128 v[138:141], v82 offset:2048
	ds_read_b128 v[142:145], v82 offset:2560
	s_waitcnt lgkmcnt(12)
	v_mfma_f32_32x32x16_bf16 v[34:49], v[158:161], v[90:93], v[34:49]
	v_exp_f32_e32 v126, v126
	v_exp_f32_e32 v127, v127
	v_exp_f32_e32 v128, v128
	v_exp_f32_e32 v129, v129
	ds_read_b128 v[178:181], v82 offset:4096
	ds_read_b128 v[182:185], v82 offset:4608
	s_waitcnt lgkmcnt(12)
	v_mfma_f32_32x32x16_bf16 v[18:33], v[150:153], v[94:97], v[18:33]
	v_exp_f32_e32 v98, v98
	v_exp_f32_e32 v99, v99
	v_exp_f32_e32 v100, v100
	v_exp_f32_e32 v101, v101
	ds_read_b128 v[186:189], v82 offset:6144
	ds_read_b128 v[130:133], v82 offset:6656
	s_waitcnt lgkmcnt(12)
	v_mfma_f32_32x32x16_bf16 v[34:49], v[150:153], v[66:69], v[34:49]
	v_exp_f32_e32 v102, v102
	v_exp_f32_e32 v103, v103
	v_exp_f32_e32 v104, v104
	v_exp_f32_e32 v105, v105
	s_waitcnt lgkmcnt(10)
	v_mfma_f32_32x32x16_bf16 v[18:33], v[146:149], v[70:73], v[18:33]
	v_exp_f32_e32 v106, v106
	v_exp_f32_e32 v107, v107
	v_exp_f32_e32 v108, v108
	v_exp_f32_e32 v109, v109
	s_waitcnt lgkmcnt(8)
	v_mfma_f32_32x32x16_bf16 v[34:49], v[146:149], v[74:77], v[34:49]
	s_waitcnt vmcnt(1) lgkmcnt(0)
	s_barrier
; #define WAIT_BAR(N) asm volatile("s_waitcnt vmcnt(" #N ") lgkmcnt(0)\n\ts_barrier":::"memory")
;   #define RESC() do{}while(0)
;   #define ROT() do{sl_prev=sl_cur;sl_cur=sl_next;sl_next=(sl_next==(NSLOT-1)*SLOTB)?0:sl_next+SLOTB;}while(0)
; template<int THRL> __device__ __forceinline__ void attn_unit(int b,int h,int qb,const bf16*Q,const bf16*__restrict__ K,const bf16*__restrict__ V,bf16*O,char*shm,float m2){
;     ...
;   int t=1;
;   for(;t+5<NT;t+=2){
;     STEP(pB0,pB1,pA0,pA1,t,true,true,true);     WAIT_BAR(2); RESC(); ROT();
;     STEP(pA0,pA1,pB0,pB1,t+1,true,true,true);   WAIT_BAR(2); RESC(); ROT();
	v_lshl_add_u64 v[238:239], v[214:215], 0, s[48:49]
	s_add_i32 s98, s16, s12
	s_mov_b32 s99, m0
	s_mov_b32 m0, s98
	s_nop 0
	global_load_lds_dwordx4 v[238:239], off
	s_mov_b32 m0, s99
	s_add_i32 s0, s15, 0x2000
	s_cmpk_lg_i32 s15, 0x4000
	s_cselect_b32 s0, s0, 0
	v_add_u32_e32 v199, s16, v220
	ds_read_b64_tr_b16 v[230:231], v199 offset:24576
	ds_read_b64_tr_b16 v[232:233], v199 offset:25088
	s_waitcnt lgkmcnt(9)
	v_mfma_f32_32x32x16_bf16 v[82:97], v[78:81], v[174:177], v[50:65]
	v_exp_f32_e32 v110, v110
	v_add_f32_e32 v66, v114, v115
	v_add_f32_e32 v66, v116, v66
	v_add_f32_e32 v66, v117, v66
	v_add_f32_e32 v66, v118, v66
	v_add_f32_e32 v66, v119, v66
	v_cvt_pk_bf16_f32 v166, v114, v115
	v_cvt_pk_bf16_f32 v167, v116, v117
	ds_read_b64_tr_b16 v[114:115], v199 offset:28672
	ds_read_b64_tr_b16 v[116:117], v199 offset:29184
	v_add_f32_e32 v66, v120, v66
	v_add_f32_e32 v66, v121, v66
	v_add_f32_e32 v66, v122, v66
	v_add_f32_e32 v146, v123, v66
	s_waitcnt lgkmcnt(10)
	v_mfma_f32_32x32x16_bf16 v[66:81], v[134:137], v[174:177], v[50:65]
	v_exp_f32_e32 v111, v111
	v_cvt_pk_bf16_f32 v168, v118, v119
	v_cvt_pk_bf16_f32 v169, v120, v121
	ds_read_b64_tr_b16 v[118:119], v199 offset:25600
	ds_read_b64_tr_b16 v[120:121], v199 offset:26112
	s_waitcnt lgkmcnt(11)
	v_mfma_f32_32x32x16_bf16 v[82:97], v[138:141], v[170:173], v[82:97]
	v_exp_f32_e32 v112, v112
	v_add_f32_e32 v134, v124, v146
	v_add_f32_e32 v134, v125, v134
	v_add_f32_e32 v134, v126, v134
	v_add_f32_e32 v134, v127, v134
	v_cvt_pk_bf16_f32 v158, v122, v123
	v_cvt_pk_bf16_f32 v159, v124, v125
	ds_read_b64_tr_b16 v[122:123], v199 offset:29696
	ds_read_b64_tr_b16 v[124:125], v199 offset:30208
	s_waitcnt lgkmcnt(12)
	v_mfma_f32_32x32x16_bf16 v[66:81], v[142:145], v[170:173], v[66:81]
	v_exp_f32_e32 v113, v113
	v_add_f32_e32 v134, v128, v134
	v_add_f32_e32 v134, v129, v134
	v_add_f32_e32 v134, v98, v134
	v_add_f32_e32 v134, v99, v134
	v_cvt_pk_bf16_f32 v160, v126, v127
	v_cvt_pk_bf16_f32 v161, v128, v129
	ds_read_b64_tr_b16 v[126:127], v199 offset:26624
	ds_read_b64_tr_b16 v[128:129], v199 offset:27136
	s_waitcnt lgkmcnt(13)
	v_mfma_f32_32x32x16_bf16 v[82:97], v[178:181], v[162:165], v[82:97]
	v_add_f32_e32 v134, v100, v134
	v_add_f32_e32 v134, v101, v134
	v_add_f32_e32 v134, v102, v134
	v_add_f32_e32 v134, v103, v134
	v_cvt_pk_bf16_f32 v150, v98, v99
	v_cvt_pk_bf16_f32 v151, v100, v101
	ds_read_b64_tr_b16 v[234:235], v199 offset:30720
	ds_read_b64_tr_b16 v[236:237], v199 offset:31232
	s_waitcnt lgkmcnt(14)
	v_mfma_f32_32x32x16_bf16 v[66:81], v[182:185], v[162:165], v[66:81]
	v_add_f32_e32 v98, v104, v134
	v_add_f32_e32 v98, v105, v98
	v_add_f32_e32 v98, v106, v98
	v_add_f32_e32 v98, v107, v98
	v_cvt_pk_bf16_f32 v152, v102, v103
	v_cvt_pk_bf16_f32 v153, v104, v105
	ds_read_b64_tr_b16 v[102:103], v199 offset:27648
	ds_read_b64_tr_b16 v[104:105], v199 offset:28160
	s_waitcnt lgkmcnt(14)
	v_mfma_f32_32x32x16_bf16 v[82:97], v[186:189], v[154:157], v[82:97]
	v_add_f32_e32 v98, v108, v98
	v_add_f32_e32 v98, v109, v98
	v_add_f32_e32 v98, v110, v98
	v_add_f32_e32 v98, v111, v98
	v_cvt_pk_bf16_f32 v146, v106, v107
	v_cvt_pk_bf16_f32 v147, v108, v109
	ds_read_b64_tr_b16 v[106:107], v199 offset:31744
	ds_read_b64_tr_b16 v[108:109], v199 offset:32256
	v_mfma_f32_32x32x16_bf16 v[66:81], v[130:133], v[154:157], v[66:81]
	v_add_f32_e32 v98, v112, v98
	v_add_f32_e32 v98, v113, v98
	v_add_f32_e32 v98, 0, v98
	v_cvt_pk_bf16_f32 v148, v110, v111
	v_cvt_pk_bf16_f32 v149, v112, v113
	v_add_f32_e32 v199, v190, v98
	v_lshl_add_u64 v[216:217], v[216:217], 0, s[46:47]
	s_add_i32 s16, s0, s4
	s_mov_b32 s17, m0
	s_mov_b32 m0, s16
	s_nop 0
	global_load_lds_dwordx4 v[216:217], off
	s_mov_b32 m0, s17
	s_waitcnt lgkmcnt(14)
	v_mfma_f32_32x32x16_bf16 v[18:33], v[166:169], v[230:233], v[18:33]
	v_exp_f32_e32 v82, v82
	v_exp_f32_e32 v83, v83
	v_exp_f32_e32 v84, v84
	v_exp_f32_e32 v85, v85
	s_waitcnt lgkmcnt(12)
	v_mfma_f32_32x32x16_bf16 v[34:49], v[166:169], v[114:117], v[34:49]
	v_exp_f32_e32 v86, v86
	v_exp_f32_e32 v87, v87
	v_exp_f32_e32 v88, v88
	v_exp_f32_e32 v89, v89
	v_add_u32_e32 v110, s0, v219
	ds_read_b128 v[98:101], v110
	ds_read_b128 v[182:185], v110 offset:512
	s_waitcnt lgkmcnt(12)
	v_mfma_f32_32x32x16_bf16 v[18:33], v[158:161], v[118:121], v[18:33]
	v_exp_f32_e32 v90, v90
	v_exp_f32_e32 v91, v91
	v_exp_f32_e32 v92, v92
	v_exp_f32_e32 v93, v93
	ds_read_b128 v[186:189], v110 offset:2048
	ds_read_b128 v[178:181], v110 offset:2560
	s_waitcnt lgkmcnt(12)
	v_mfma_f32_32x32x16_bf16 v[34:49], v[158:161], v[122:125], v[34:49]
	v_exp_f32_e32 v94, v94
	v_exp_f32_e32 v95, v95
	v_exp_f32_e32 v96, v96
	v_exp_f32_e32 v97, v97
	ds_read_b128 v[142:145], v110 offset:4096
	ds_read_b128 v[138:141], v110 offset:4608
	s_waitcnt lgkmcnt(12)
	v_mfma_f32_32x32x16_bf16 v[18:33], v[150:153], v[126:129], v[18:33]
	v_exp_f32_e32 v66, v66
	v_exp_f32_e32 v67, v67
	v_exp_f32_e32 v68, v68
	v_exp_f32_e32 v69, v69
	ds_read_b128 v[134:137], v110 offset:6144
	ds_read_b128 v[130:133], v110 offset:6656
	s_waitcnt lgkmcnt(12)
	v_mfma_f32_32x32x16_bf16 v[34:49], v[150:153], v[234:237], v[34:49]
	v_exp_f32_e32 v70, v70
	v_exp_f32_e32 v71, v71
	v_exp_f32_e32 v72, v72
	v_exp_f32_e32 v73, v73
	s_waitcnt lgkmcnt(10)
	v_mfma_f32_32x32x16_bf16 v[18:33], v[146:149], v[102:105], v[18:33]
	v_exp_f32_e32 v74, v74
	v_exp_f32_e32 v75, v75
	v_exp_f32_e32 v76, v76
	v_exp_f32_e32 v77, v77
	s_waitcnt lgkmcnt(8)
	v_mfma_f32_32x32x16_bf16 v[34:49], v[146:149], v[106:109], v[34:49]
	s_add_i32 s18, s0, 0x2000
	s_waitcnt vmcnt(1) lgkmcnt(0)
	s_barrier
; #define WAIT_BAR(N) asm volatile("s_waitcnt vmcnt(" #N ") lgkmcnt(0)\n\ts_barrier":::"memory")
;   #define RESC() do{}while(0)
;   #define ROT() do{sl_prev=sl_cur;sl_cur=sl_next;sl_next=(sl_next==(NSLOT-1)*SLOTB)?0:sl_next+SLOTB;}while(0)
;   #define ENDW(tt) do{ if((tt)+3<NT){WAIT_BAR(2);} else if((tt)+2<NT){WAIT_BAR(1);} else {WAIT_BAR(0);} }while(0)
; template<int THRL> __device__ __forceinline__ void attn_unit(int b,int h,int qb,const bf16*Q,const bf16*__restrict__ K,const bf16*__restrict__ V,bf16*O,char*shm,float m2){
;     ...
;   int t=1;
;   for(;t+5<NT;t+=2){
;     STEP(pB0,pB1,pA0,pA1,t,true,true,true);     WAIT_BAR(2); RESC(); ROT();
;     STEP(pA0,pA1,pB0,pB1,t+1,true,true,true);   WAIT_BAR(2); RESC(); ROT();
;   }
;     ...
;   for(;t+1<NT;t+=2){
;     STEP(pB0,pB1,pA0,pA1,t,(t+3<NT),(t+1<NT),(t+1<NT));       ENDW(t);   RESC(); ROT();
	s_mov_b64 s[100:101], 0x10000
	v_lshl_add_u64 v[238:239], v[214:215], 0, s[100:101]
	s_add_i32 s98, s15, s12
	s_mov_b32 s99, m0
	s_mov_b32 m0, s98
	s_nop 0
	global_load_lds_dwordx4 v[238:239], off
	s_mov_b32 m0, s99
	s_cmpk_lg_i32 s0, 0x4000
	s_mov_b32 s17, s15
	s_cselect_b32 s15, s18, 0
	s_add_i32 s14, s14, 2
	v_lshl_add_u64 v[214:215], v[214:215], 0, s[46:47]
	s_mov_b32 s16, s0
	s_cmpk_gt_u32 s14, 0x78
	s_cbranch_scc0 .LBB0_829
	v_exp_f32_e32 v78, v78
	v_exp_f32_e32 v79, v79
	v_exp_f32_e32 v80, v80
	v_exp_f32_e32 v81, v81
	s_and_b32 s0, s13, 0x3fffffc0
	s_lshl_b32 s0, s0, 2
	s_add_i32 s0, s0, 0
	ds_read_b64_tr_b16 v[214:215], v220 offset:40960
	ds_read_b64_tr_b16 v[216:217], v220 offset:41472
	v_add_f32_e32 v102, v82, v83
	v_add_f32_e32 v102, v84, v102
	v_add_f32_e32 v102, v85, v102
	v_add_f32_e32 v102, v86, v102
	v_add_f32_e32 v102, v87, v102
	v_cvt_pk_bf16_f32 v166, v82, v83
	v_cvt_pk_bf16_f32 v167, v84, v85
	s_waitcnt lgkmcnt(9)
	v_mfma_f32_32x32x16_bf16 v[114:129], v[98:101], v[174:177], v[50:65]
	ds_read_b64_tr_b16 v[82:83], v220 offset:45056
	ds_read_b64_tr_b16 v[84:85], v220 offset:45568
	v_add_f32_e32 v98, v88, v102
	v_add_f32_e32 v98, v89, v98
	v_add_f32_e32 v98, v90, v98
	v_add_f32_e32 v146, v91, v98
	v_cvt_pk_bf16_f32 v168, v86, v87
	v_cvt_pk_bf16_f32 v169, v88, v89
	s_waitcnt lgkmcnt(10)
	v_mfma_f32_32x32x16_bf16 v[98:113], v[182:185], v[174:177], v[50:65]
	ds_read_b64_tr_b16 v[86:87], v220 offset:41984
	ds_read_b64_tr_b16 v[88:89], v220 offset:42496
	v_add_f32_e32 v146, v92, v146
	v_add_f32_e32 v146, v93, v146
	v_add_f32_e32 v146, v94, v146
	v_add_f32_e32 v146, v95, v146
	v_cvt_pk_bf16_f32 v158, v90, v91
	v_cvt_pk_bf16_f32 v159, v92, v93
	s_waitcnt lgkmcnt(11)
	v_mfma_f32_32x32x16_bf16 v[114:129], v[186:189], v[170:173], v[114:129]
	ds_read_b64_tr_b16 v[90:91], v220 offset:46080
	ds_read_b64_tr_b16 v[92:93], v220 offset:46592
	v_add_f32_e32 v146, v96, v146
	v_add_f32_e32 v146, v97, v146
	v_add_f32_e32 v146, v66, v146
	v_add_f32_e32 v146, v67, v146
	v_cvt_pk_bf16_f32 v160, v94, v95
	v_cvt_pk_bf16_f32 v161, v96, v97
	s_waitcnt lgkmcnt(12)
	v_mfma_f32_32x32x16_bf16 v[98:113], v[178:181], v[170:173], v[98:113]
	ds_read_b64_tr_b16 v[94:95], v220 offset:43008
	ds_read_b64_tr_b16 v[96:97], v220 offset:43520
	s_waitcnt lgkmcnt(13)
	v_mfma_f32_32x32x16_bf16 v[114:129], v[142:145], v[162:165], v[114:129]
	v_add_f32_e32 v142, v68, v146
	v_add_f32_e32 v142, v69, v142
	v_add_f32_e32 v142, v70, v142
	v_add_f32_e32 v142, v71, v142
	v_cvt_pk_bf16_f32 v150, v66, v67
	v_cvt_pk_bf16_f32 v151, v68, v69
	ds_read_b64_tr_b16 v[66:67], v220 offset:47104
	ds_read_b64_tr_b16 v[68:69], v220 offset:47616
	s_waitcnt lgkmcnt(14)
	v_mfma_f32_32x32x16_bf16 v[98:113], v[138:141], v[162:165], v[98:113]
	v_add_f32_e32 v138, v72, v142
	v_add_f32_e32 v138, v73, v138
	v_add_f32_e32 v138, v74, v138
	v_add_f32_e32 v138, v75, v138
	v_cvt_pk_bf16_f32 v152, v70, v71
	v_cvt_pk_bf16_f32 v153, v72, v73
	ds_read_b64_tr_b16 v[70:71], v220 offset:44032
	ds_read_b64_tr_b16 v[72:73], v220 offset:44544
	s_waitcnt lgkmcnt(14)
	v_mfma_f32_32x32x16_bf16 v[114:129], v[134:137], v[154:157], v[114:129]
	v_add_f32_e32 v134, v76, v138
	v_add_f32_e32 v134, v77, v134
	v_add_f32_e32 v134, v78, v134
	v_add_f32_e32 v134, v79, v134
	v_cvt_pk_bf16_f32 v146, v74, v75
	v_cvt_pk_bf16_f32 v147, v76, v77
	ds_read_b64_tr_b16 v[74:75], v220 offset:48128
	ds_read_b64_tr_b16 v[76:77], v220 offset:48640
	v_mfma_f32_32x32x16_bf16 v[98:113], v[130:133], v[154:157], v[98:113]
	v_add_f32_e32 v130, v80, v134
	v_add_f32_e32 v130, v81, v130
	v_add_f32_e32 v130, 0, v130
	v_cvt_pk_bf16_f32 v148, v78, v79
	v_cvt_pk_bf16_f32 v149, v80, v81
	s_mov_b64 s[12:13], 0x1f0000
	s_cmp_lg_u32 0, -1
	v_lshl_add_u64 v[78:79], v[210:211], 0, s[12:13]
	s_cselect_b32 s12, 0, 0
	s_add_i32 s12, s12, s5
	s_add_i32 s5, s12, 0x8000
	s_mov_b32 s13, m0
	s_mov_b32 m0, s5
	s_nop 0
	global_load_lds_dwordx4 v[78:79], off
	s_mov_b32 m0, s13
	v_add_f32_e32 v190, v199, v130
	s_waitcnt lgkmcnt(14)
	v_mfma_f32_32x32x16_bf16 v[18:33], v[166:169], v[214:217], v[18:33]
	v_exp_f32_e32 v114, v114
	v_exp_f32_e32 v115, v115
	v_exp_f32_e32 v116, v116
	v_exp_f32_e32 v117, v117
	s_waitcnt lgkmcnt(12)
	v_mfma_f32_32x32x16_bf16 v[34:49], v[166:169], v[82:85], v[34:49]
	v_exp_f32_e32 v118, v118
	v_exp_f32_e32 v119, v119
	v_exp_f32_e32 v120, v120
	v_exp_f32_e32 v121, v121
	ds_read_b128 v[78:81], v219 offset:8192
	ds_read_b128 v[178:181], v219 offset:8704
	s_waitcnt lgkmcnt(12)
	v_mfma_f32_32x32x16_bf16 v[18:33], v[158:161], v[86:89], v[18:33]
	v_exp_f32_e32 v122, v122
	v_exp_f32_e32 v123, v123
	v_exp_f32_e32 v124, v124
	v_exp_f32_e32 v125, v125
	ds_read_b128 v[86:89], v219 offset:10240
	ds_read_b128 v[182:185], v219 offset:10752
	s_waitcnt lgkmcnt(12)
	v_mfma_f32_32x32x16_bf16 v[34:49], v[158:161], v[90:93], v[34:49]
	v_exp_f32_e32 v126, v126
	v_exp_f32_e32 v127, v127
	v_exp_f32_e32 v128, v128
	v_exp_f32_e32 v129, v129
	ds_read_b128 v[90:93], v219 offset:12288
	ds_read_b128 v[186:189], v219 offset:12800
	s_waitcnt lgkmcnt(12)
	v_mfma_f32_32x32x16_bf16 v[18:33], v[150:153], v[94:97], v[18:33]
	v_exp_f32_e32 v98, v98
	v_exp_f32_e32 v99, v99
	v_exp_f32_e32 v100, v100
	v_exp_f32_e32 v101, v101
	ds_read_b128 v[94:97], v219 offset:14336
	ds_read_b128 v[82:85], v219 offset:14848
	s_waitcnt lgkmcnt(12)
	v_mfma_f32_32x32x16_bf16 v[34:49], v[150:153], v[66:69], v[34:49]
	v_exp_f32_e32 v102, v102
	v_exp_f32_e32 v103, v103
	v_exp_f32_e32 v104, v104
	v_exp_f32_e32 v105, v105
	s_waitcnt lgkmcnt(10)
	v_mfma_f32_32x32x16_bf16 v[18:33], v[146:149], v[70:73], v[18:33]
	v_exp_f32_e32 v106, v106
	v_exp_f32_e32 v107, v107
	v_exp_f32_e32 v108, v108
	v_exp_f32_e32 v109, v109
	s_waitcnt lgkmcnt(8)
	v_mfma_f32_32x32x16_bf16 v[34:49], v[146:149], v[74:77], v[34:49]
	v_exp_f32_e32 v110, v110
	v_exp_f32_e32 v111, v111
	v_exp_f32_e32 v112, v112
	v_exp_f32_e32 v113, v113
	s_waitcnt vmcnt(1) lgkmcnt(0)
	s_barrier
; #define WAIT_BAR(N) asm volatile("s_waitcnt vmcnt(" #N ") lgkmcnt(0)\n\ts_barrier":::"memory")
;   #define RESC() do{}while(0)
;   #define ROT() do{sl_prev=sl_cur;sl_cur=sl_next;sl_next=(sl_next==(NSLOT-1)*SLOTB)?0:sl_next+SLOTB;}while(0)
;   #define ENDW(tt) do{ if((tt)+3<NT){WAIT_BAR(2);} else if((tt)+2<NT){WAIT_BAR(1);} else {WAIT_BAR(0);} }while(0)
; template<int THRL> __device__ __forceinline__ void attn_unit(int b,int h,int qb,const bf16*Q,const bf16*__restrict__ K,const bf16*__restrict__ V,bf16*O,char*shm,float m2){
;     ...
;   int t=1;
;   for(;t+5<NT;t+=2){
;     STEP(pB0,pB1,pA0,pA1,t,true,true,true);     WAIT_BAR(2); RESC(); ROT();
;     STEP(pA0,pA1,pB0,pB1,t+1,true,true,true);   WAIT_BAR(2); RESC(); ROT();
;   }
;     ...
;   for(;t+1<NT;t+=2){
;     STEP(pB0,pB1,pA0,pA1,t,(t+3<NT),(t+1<NT),(t+1<NT));       ENDW(t);   RESC(); ROT();
;     STEP(pA0,pA1,pB0,pB1,t+1,(t+4<NT),(t+2<NT),(t+2<NT));     ENDW(t+1); RESC(); ROT();
	v_lshl_add_u64 v[238:239], v[212:213], 0, s[50:51]
	s_mov_b32 s98, s12
	s_mov_b32 s99, m0
	s_mov_b32 m0, s98
	s_nop 0
	global_load_lds_dwordx4 v[238:239], off
	s_mov_b32 m0, s99
	ds_read_b64_tr_b16 v[214:215], v220 offset:24576
	ds_read_b64_tr_b16 v[216:217], v220 offset:25088
	v_add_f32_e32 v66, v114, v115
	v_add_f32_e32 v66, v116, v66
	v_add_f32_e32 v66, v117, v66
	v_add_f32_e32 v66, v118, v66
	v_add_f32_e32 v66, v119, v66
	v_cvt_pk_bf16_f32 v166, v114, v115
	v_cvt_pk_bf16_f32 v167, v116, v117
	s_waitcnt lgkmcnt(9)
	v_mfma_f32_32x32x16_bf16 v[130:145], v[78:81], v[174:177], v[50:65]
	ds_read_b64_tr_b16 v[114:115], v220 offset:28672
	ds_read_b64_tr_b16 v[116:117], v220 offset:29184
	v_add_f32_e32 v66, v120, v66
	v_add_f32_e32 v66, v121, v66
	v_add_f32_e32 v66, v122, v66
	v_add_f32_e32 v146, v123, v66
	s_waitcnt lgkmcnt(10)
	v_mfma_f32_32x32x16_bf16 v[66:81], v[178:181], v[174:177], v[50:65]
	v_cvt_pk_bf16_f32 v168, v118, v119
	v_cvt_pk_bf16_f32 v169, v120, v121
	ds_read_b64_tr_b16 v[118:119], v220 offset:25600
	ds_read_b64_tr_b16 v[120:121], v220 offset:26112
	s_waitcnt lgkmcnt(11)
	v_mfma_f32_32x32x16_bf16 v[130:145], v[86:89], v[170:173], v[130:145]
	v_add_f32_e32 v86, v124, v146
	v_add_f32_e32 v86, v125, v86
	v_add_f32_e32 v86, v126, v86
	v_add_f32_e32 v146, v127, v86
	v_cvt_pk_bf16_f32 v158, v122, v123
	v_cvt_pk_bf16_f32 v159, v124, v125
	ds_read_b64_tr_b16 v[86:87], v220 offset:29696
	ds_read_b64_tr_b16 v[88:89], v220 offset:30208
	s_waitcnt lgkmcnt(12)
	v_mfma_f32_32x32x16_bf16 v[66:81], v[182:185], v[170:173], v[66:81]
	v_add_f32_e32 v122, v128, v146
	v_add_f32_e32 v122, v129, v122
	v_add_f32_e32 v122, v98, v122
	v_add_f32_e32 v146, v99, v122
	v_cvt_pk_bf16_f32 v160, v126, v127
	v_cvt_pk_bf16_f32 v161, v128, v129
	ds_read_b64_tr_b16 v[122:123], v220 offset:26624
	ds_read_b64_tr_b16 v[124:125], v220 offset:27136
	s_waitcnt lgkmcnt(13)
	v_mfma_f32_32x32x16_bf16 v[130:145], v[90:93], v[162:165], v[130:145]
	v_add_f32_e32 v90, v100, v146
	v_add_f32_e32 v90, v101, v90
	v_add_f32_e32 v90, v102, v90
	v_add_f32_e32 v126, v103, v90
	v_cvt_pk_bf16_f32 v150, v98, v99
	v_cvt_pk_bf16_f32 v151, v100, v101
	ds_read_b64_tr_b16 v[90:91], v220 offset:30720
	ds_read_b64_tr_b16 v[92:93], v220 offset:31232
	s_waitcnt lgkmcnt(14)
	v_mfma_f32_32x32x16_bf16 v[66:81], v[186:189], v[162:165], v[66:81]
	v_add_f32_e32 v98, v104, v126
	v_add_f32_e32 v98, v105, v98
	v_add_f32_e32 v98, v106, v98
	v_add_f32_e32 v98, v107, v98
	v_cvt_pk_bf16_f32 v152, v102, v103
	v_cvt_pk_bf16_f32 v153, v104, v105
	ds_read_b64_tr_b16 v[102:103], v220 offset:27648
	ds_read_b64_tr_b16 v[104:105], v220 offset:28160
	s_waitcnt lgkmcnt(14)
	v_mfma_f32_32x32x16_bf16 v[130:145], v[94:97], v[154:157], v[130:145]
	v_add_f32_e32 v94, v108, v98
	v_add_f32_e32 v94, v109, v94
	v_add_f32_e32 v94, v110, v94
	v_add_f32_e32 v98, v111, v94
	v_cvt_pk_bf16_f32 v146, v106, v107
	v_cvt_pk_bf16_f32 v147, v108, v109
	ds_read_b64_tr_b16 v[94:95], v220 offset:31744
	ds_read_b64_tr_b16 v[96:97], v220 offset:32256
	v_mfma_f32_32x32x16_bf16 v[66:81], v[82:85], v[154:157], v[66:81]
	v_add_f32_e32 v82, v112, v98
	v_add_f32_e32 v82, v113, v82
	v_add_f32_e32 v82, 0, v82
	v_cvt_pk_bf16_f32 v148, v110, v111
	v_cvt_pk_bf16_f32 v149, v112, v113
	s_nop 0
	v_add_f32_e32 v190, v190, v82
	v_lshl_add_u64 v[238:239], v[212:213], 0, s[52:53]
	s_mov_b64 s[14:15], 0x1f4000
	v_lshl_add_u64 v[82:83], v[210:211], 0, s[14:15]
	s_add_i32 s12, s12, 0xa000
	s_mov_b32 s13, m0
	s_mov_b32 m0, s12
	s_nop 0
	global_load_lds_dwordx4 v[82:83], off
	s_mov_b32 m0, s13
	s_waitcnt lgkmcnt(14)
	v_mfma_f32_32x32x16_bf16 v[18:33], v[166:169], v[214:217], v[18:33]
	v_exp_f32_e32 v130, v130
	v_exp_f32_e32 v131, v131
	v_exp_f32_e32 v132, v132
	v_exp_f32_e32 v133, v133
	s_waitcnt lgkmcnt(12)
	v_mfma_f32_32x32x16_bf16 v[34:49], v[166:169], v[114:117], v[34:49]
	v_exp_f32_e32 v134, v134
	v_exp_f32_e32 v135, v135
	v_exp_f32_e32 v136, v136
	v_exp_f32_e32 v137, v137
	ds_read_b128 v[82:85], v219 offset:16384
	ds_read_b128 v[106:109], v219 offset:16896
	s_waitcnt lgkmcnt(12)
	v_mfma_f32_32x32x16_bf16 v[18:33], v[158:161], v[118:121], v[18:33]
	v_exp_f32_e32 v138, v138
	v_exp_f32_e32 v139, v139
	v_exp_f32_e32 v140, v140
	v_exp_f32_e32 v141, v141
	ds_read_b128 v[110:113], v219 offset:18432
	ds_read_b128 v[178:181], v219 offset:18944
	s_waitcnt lgkmcnt(12)
	v_mfma_f32_32x32x16_bf16 v[34:49], v[158:161], v[86:89], v[34:49]
	v_exp_f32_e32 v142, v142
	v_exp_f32_e32 v143, v143
	v_exp_f32_e32 v144, v144
	v_exp_f32_e32 v145, v145
	ds_read_b128 v[182:185], v219 offset:20480
	ds_read_b128 v[186:189], v219 offset:20992
	s_waitcnt lgkmcnt(12)
	v_mfma_f32_32x32x16_bf16 v[18:33], v[150:153], v[122:125], v[18:33]
	v_exp_f32_e32 v66, v66
	v_exp_f32_e32 v67, v67
	v_exp_f32_e32 v68, v68
	v_exp_f32_e32 v69, v69
	ds_read_b128 v[212:215], v219 offset:22528
	ds_read_b128 v[98:101], v219 offset:23040
	s_waitcnt lgkmcnt(12)
	v_mfma_f32_32x32x16_bf16 v[34:49], v[150:153], v[90:93], v[34:49]
	v_exp_f32_e32 v70, v70
	v_exp_f32_e32 v71, v71
	v_exp_f32_e32 v72, v72
	v_exp_f32_e32 v73, v73
	s_waitcnt lgkmcnt(10)
	v_mfma_f32_32x32x16_bf16 v[18:33], v[146:149], v[102:105], v[18:33]
	v_exp_f32_e32 v74, v74
	v_exp_f32_e32 v75, v75
	v_exp_f32_e32 v76, v76
	v_exp_f32_e32 v77, v77
	s_waitcnt lgkmcnt(8)
	v_mfma_f32_32x32x16_bf16 v[34:49], v[146:149], v[94:97], v[34:49]
	v_exp_f32_e32 v78, v78
	v_exp_f32_e32 v79, v79
	v_exp_f32_e32 v80, v80
	v_exp_f32_e32 v81, v81
	s_waitcnt vmcnt(1) lgkmcnt(0)
	s_barrier
; #define WAIT_BAR(N) asm volatile("s_waitcnt vmcnt(" #N ") lgkmcnt(0)\n\ts_barrier":::"memory")
;   #define RESC() do{}while(0)
;   #define ROT() do{sl_prev=sl_cur;sl_cur=sl_next;sl_next=(sl_next==(NSLOT-1)*SLOTB)?0:sl_next+SLOTB;}while(0)
;   #define ENDW(tt) do{ if((tt)+3<NT){WAIT_BAR(2);} else if((tt)+2<NT){WAIT_BAR(1);} else {WAIT_BAR(0);} }while(0)
; template<int THRL> __device__ __forceinline__ void attn_unit(int b,int h,int qb,const bf16*Q,const bf16*__restrict__ K,const bf16*__restrict__ V,bf16*O,char*shm,float m2){
;     ...
;   int t=1;
;   for(;t+5<NT;t+=2){
;     STEP(pB0,pB1,pA0,pA1,t,true,true,true);     WAIT_BAR(2); RESC(); ROT();
;     STEP(pA0,pA1,pB0,pB1,t+1,true,true,true);   WAIT_BAR(2); RESC(); ROT();
;   }
;     ...
;   for(;t+1<NT;t+=2){
;     STEP(pB0,pB1,pA0,pA1,t,(t+3<NT),(t+1<NT),(t+1<NT));       ENDW(t);   RESC(); ROT();
;     STEP(pA0,pA1,pB0,pB1,t+1,(t+4<NT),(t+2<NT),(t+2<NT));     ENDW(t+1); RESC(); ROT();
;   }
	s_add_i32 s98, s5, 0xffffa000
	s_mov_b32 s99, m0
	s_mov_b32 m0, s98
	s_nop 0
	global_load_lds_dwordx4 v[238:239], off
	s_mov_b32 m0, s99
	ds_read_b64_tr_b16 v[102:103], v220 offset:32768
	ds_read_b64_tr_b16 v[104:105], v220 offset:33280
	v_add_f32_e32 v86, v130, v131
	v_add_f32_e32 v86, v132, v86
	v_add_f32_e32 v86, v133, v86
	v_add_f32_e32 v86, v134, v86
	v_add_f32_e32 v86, v135, v86
	v_cvt_pk_bf16_f32 v166, v130, v131
	v_cvt_pk_bf16_f32 v167, v132, v133
	s_waitcnt lgkmcnt(9)
	v_mfma_f32_32x32x16_bf16 v[114:129], v[82:85], v[174:177], v[50:65]
	ds_read_b64_tr_b16 v[130:131], v220 offset:36864
	ds_read_b64_tr_b16 v[132:133], v220 offset:37376
	v_add_f32_e32 v82, v136, v86
	v_add_f32_e32 v82, v137, v82
	v_add_f32_e32 v82, v138, v82
	v_add_f32_e32 v146, v139, v82
	v_cvt_pk_bf16_f32 v168, v134, v135
	v_cvt_pk_bf16_f32 v169, v136, v137
	s_waitcnt lgkmcnt(10)
	v_mfma_f32_32x32x16_bf16 v[82:97], v[106:109], v[174:177], v[50:65]
	ds_read_b64_tr_b16 v[106:107], v220 offset:33792
	ds_read_b64_tr_b16 v[108:109], v220 offset:34304
	s_waitcnt lgkmcnt(11)
	v_mfma_f32_32x32x16_bf16 v[114:129], v[110:113], v[170:173], v[114:129]
	v_add_f32_e32 v110, v140, v146
	v_add_f32_e32 v110, v141, v110
	v_add_f32_e32 v110, v142, v110
	v_add_f32_e32 v134, v143, v110
	v_cvt_pk_bf16_f32 v158, v138, v139
	v_cvt_pk_bf16_f32 v159, v140, v141
	ds_read_b64_tr_b16 v[110:111], v220 offset:37888
	ds_read_b64_tr_b16 v[112:113], v220 offset:38400
	v_add_f32_e32 v134, v144, v134
	v_add_f32_e32 v134, v145, v134
	v_add_f32_e32 v134, v66, v134
	v_add_f32_e32 v138, v67, v134
	v_cvt_pk_bf16_f32 v160, v142, v143
	v_cvt_pk_bf16_f32 v161, v144, v145
	s_waitcnt lgkmcnt(12)
	v_mfma_f32_32x32x16_bf16 v[82:97], v[178:181], v[170:173], v[82:97]
	ds_read_b64_tr_b16 v[134:135], v220 offset:34816
	ds_read_b64_tr_b16 v[136:137], v220 offset:35328
	v_add_f32_e32 v138, v68, v138
	v_add_f32_e32 v138, v69, v138
	v_add_f32_e32 v138, v70, v138
	v_add_f32_e32 v138, v71, v138
	v_cvt_pk_bf16_f32 v150, v66, v67
	v_cvt_pk_bf16_f32 v151, v68, v69
	s_waitcnt lgkmcnt(13)
	v_mfma_f32_32x32x16_bf16 v[114:129], v[182:185], v[162:165], v[114:129]
	ds_read_b64_tr_b16 v[66:67], v220 offset:38912
	ds_read_b64_tr_b16 v[68:69], v220 offset:39424
	v_add_f32_e32 v138, v72, v138
	v_add_f32_e32 v138, v73, v138
	v_add_f32_e32 v138, v74, v138
	v_add_f32_e32 v138, v75, v138
	v_cvt_pk_bf16_f32 v152, v70, v71
	v_cvt_pk_bf16_f32 v153, v72, v73
	s_waitcnt lgkmcnt(14)
	v_mfma_f32_32x32x16_bf16 v[82:97], v[186:189], v[162:165], v[82:97]
	ds_read_b64_tr_b16 v[70:71], v220 offset:35840
	ds_read_b64_tr_b16 v[72:73], v220 offset:36352
	v_add_f32_e32 v138, v76, v138
	v_add_f32_e32 v138, v77, v138
	v_add_f32_e32 v138, v78, v138
	v_add_f32_e32 v138, v79, v138
	v_cvt_pk_bf16_f32 v146, v74, v75
	v_cvt_pk_bf16_f32 v147, v76, v77
	s_waitcnt lgkmcnt(14)
	v_mfma_f32_32x32x16_bf16 v[114:129], v[212:215], v[154:157], v[114:129]
	ds_read_b64_tr_b16 v[74:75], v220 offset:39936
	ds_read_b64_tr_b16 v[76:77], v220 offset:40448
	v_mfma_f32_32x32x16_bf16 v[82:97], v[98:101], v[154:157], v[82:97]
	v_add_f32_e32 v98, v80, v138
	v_add_f32_e32 v98, v81, v98
	v_add_f32_e32 v98, 0, v98
	v_cvt_pk_bf16_f32 v148, v78, v79
	v_cvt_pk_bf16_f32 v149, v80, v81
	v_lshl_add_u64 v[78:79], v[210:211], 0, s[50:51]
	s_mov_b32 s12, m0
	s_mov_b32 m0, s4
	s_nop 0
	global_load_lds_dwordx4 v[78:79], off
	s_mov_b32 m0, s12
	v_add_f32_e32 v190, v190, v98
	s_waitcnt lgkmcnt(14)
	v_mfma_f32_32x32x16_bf16 v[18:33], v[166:169], v[102:105], v[18:33]
	v_exp_f32_e32 v114, v114
	v_exp_f32_e32 v115, v115
	v_exp_f32_e32 v116, v116
	v_exp_f32_e32 v117, v117
	s_waitcnt lgkmcnt(12)
	v_mfma_f32_32x32x16_bf16 v[34:49], v[166:169], v[130:133], v[34:49]
	v_exp_f32_e32 v118, v118
	v_exp_f32_e32 v119, v119
	v_exp_f32_e32 v120, v120
	v_exp_f32_e32 v121, v121
	ds_read_b128 v[78:81], v219
	ds_read_b128 v[138:141], v219 offset:512
	s_waitcnt lgkmcnt(12)
	v_mfma_f32_32x32x16_bf16 v[18:33], v[158:161], v[106:109], v[18:33]
	v_exp_f32_e32 v122, v122
	v_exp_f32_e32 v123, v123
	v_exp_f32_e32 v124, v124
	v_exp_f32_e32 v125, v125
	ds_read_b128 v[142:145], v219 offset:2048
	ds_read_b128 v[178:181], v219 offset:2560
	s_waitcnt lgkmcnt(12)
	v_mfma_f32_32x32x16_bf16 v[34:49], v[158:161], v[110:113], v[34:49]
	v_exp_f32_e32 v126, v126
	v_exp_f32_e32 v127, v127
	v_exp_f32_e32 v128, v128
	v_exp_f32_e32 v129, v129
	ds_read_b128 v[182:185], v219 offset:4096
	ds_read_b128 v[186:189], v219 offset:4608
	s_waitcnt lgkmcnt(12)
	v_mfma_f32_32x32x16_bf16 v[18:33], v[150:153], v[134:137], v[18:33]
	v_exp_f32_e32 v82, v82
	v_exp_f32_e32 v83, v83
	v_exp_f32_e32 v84, v84
	v_exp_f32_e32 v85, v85
	ds_read_b128 v[134:137], v219 offset:6144
	ds_read_b128 v[130:133], v219 offset:6656
	s_waitcnt lgkmcnt(12)
	v_mfma_f32_32x32x16_bf16 v[34:49], v[150:153], v[66:69], v[34:49]
	v_exp_f32_e32 v86, v86
	v_exp_f32_e32 v87, v87
	v_exp_f32_e32 v88, v88
	v_exp_f32_e32 v89, v89
	s_waitcnt lgkmcnt(10)
	v_mfma_f32_32x32x16_bf16 v[18:33], v[146:149], v[70:73], v[18:33]
	v_exp_f32_e32 v90, v90
	v_exp_f32_e32 v91, v91
	v_exp_f32_e32 v92, v92
	v_exp_f32_e32 v93, v93
	s_waitcnt lgkmcnt(8)
	v_mfma_f32_32x32x16_bf16 v[34:49], v[146:149], v[74:77], v[34:49]
	v_exp_f32_e32 v94, v94
	v_exp_f32_e32 v95, v95
	v_exp_f32_e32 v96, v96
	v_exp_f32_e32 v97, v97
	s_waitcnt vmcnt(1) lgkmcnt(0)
	s_barrier
; #define WAIT_BAR(N) asm volatile("s_waitcnt vmcnt(" #N ") lgkmcnt(0)\n\ts_barrier":::"memory")
;   #define RESC() do{}while(0)
;   #define ROT() do{sl_prev=sl_cur;sl_cur=sl_next;sl_next=(sl_next==(NSLOT-1)*SLOTB)?0:sl_next+SLOTB;}while(0)
;   #define ENDW(tt) do{ if((tt)+3<NT){WAIT_BAR(2);} else if((tt)+2<NT){WAIT_BAR(1);} else {WAIT_BAR(0);} }while(0)
; template<int THRL> __device__ __forceinline__ void attn_unit(int b,int h,int qb,const bf16*Q,const bf16*__restrict__ K,const bf16*__restrict__ V,bf16*O,char*shm,float m2){
;     ...
;   int t=1;
;   for(;t+5<NT;t+=2){
;     STEP(pB0,pB1,pA0,pA1,t,true,true,true);     WAIT_BAR(2); RESC(); ROT();
;     STEP(pA0,pA1,pB0,pB1,t+1,true,true,true);   WAIT_BAR(2); RESC(); ROT();
;   }
;     ...
;   for(;t+1<NT;t+=2){
;     STEP(pB0,pB1,pA0,pA1,t,(t+3<NT),(t+1<NT),(t+1<NT));       ENDW(t);   RESC(); ROT();
;     STEP(pA0,pA1,pB0,pB1,t+1,(t+4<NT),(t+2<NT),(t+2<NT));     ENDW(t+1); RESC(); ROT();
;   }
	ds_read_b64_tr_b16 v[212:213], v220 offset:40960
	ds_read_b64_tr_b16 v[214:215], v220 offset:41472
	v_add_f32_e32 v66, v114, v115
	v_add_f32_e32 v66, v116, v66
	v_add_f32_e32 v66, v117, v66
	v_add_f32_e32 v66, v118, v66
	v_add_f32_e32 v66, v119, v66
	v_cvt_pk_bf16_f32 v166, v114, v115
	v_cvt_pk_bf16_f32 v167, v116, v117
	s_waitcnt lgkmcnt(9)
	v_mfma_f32_32x32x16_bf16 v[98:113], v[78:81], v[174:177], v[50:65]
	ds_read_b64_tr_b16 v[114:115], v220 offset:45056
	ds_read_b64_tr_b16 v[116:117], v220 offset:45568
	v_add_f32_e32 v66, v120, v66
	v_add_f32_e32 v66, v121, v66
	v_add_f32_e32 v66, v122, v66
	v_add_f32_e32 v146, v123, v66
	s_waitcnt lgkmcnt(10)
	v_mfma_f32_32x32x16_bf16 v[66:81], v[138:141], v[174:177], v[50:65]
	v_cvt_pk_bf16_f32 v168, v118, v119
	v_cvt_pk_bf16_f32 v169, v120, v121
	ds_read_b64_tr_b16 v[138:139], v220 offset:41984
	ds_read_b64_tr_b16 v[140:141], v220 offset:42496
	v_add_f32_e32 v118, v124, v146
	v_add_f32_e32 v118, v125, v118
	v_add_f32_e32 v118, v126, v118
	v_add_f32_e32 v118, v127, v118
	v_cvt_pk_bf16_f32 v158, v122, v123
	v_cvt_pk_bf16_f32 v159, v124, v125
	s_waitcnt lgkmcnt(11)
	v_mfma_f32_32x32x16_bf16 v[98:113], v[142:145], v[170:173], v[98:113]
	ds_read_b64_tr_b16 v[120:121], v220 offset:46080
	ds_read_b64_tr_b16 v[122:123], v220 offset:46592
	s_waitcnt lgkmcnt(12)
	v_mfma_f32_32x32x16_bf16 v[66:81], v[178:181], v[170:173], v[66:81]
	v_add_f32_e32 v118, v128, v118
	v_add_f32_e32 v118, v129, v118
	v_add_f32_e32 v118, v82, v118
	v_add_f32_e32 v118, v83, v118
	v_cvt_pk_bf16_f32 v160, v126, v127
	v_cvt_pk_bf16_f32 v161, v128, v129
	ds_read_b64_tr_b16 v[124:125], v220 offset:43008
	ds_read_b64_tr_b16 v[126:127], v220 offset:43520
	v_add_f32_e32 v118, v84, v118
	v_add_f32_e32 v118, v85, v118
	v_add_f32_e32 v118, v86, v118
	v_add_f32_e32 v118, v87, v118
	v_cvt_pk_bf16_f32 v150, v82, v83
	v_cvt_pk_bf16_f32 v151, v84, v85
	s_waitcnt lgkmcnt(13)
	v_mfma_f32_32x32x16_bf16 v[98:113], v[182:185], v[162:165], v[98:113]
	ds_read_b64_tr_b16 v[82:83], v220 offset:47104
	ds_read_b64_tr_b16 v[84:85], v220 offset:47616
	s_waitcnt lgkmcnt(14)
	v_mfma_f32_32x32x16_bf16 v[66:81], v[186:189], v[162:165], v[66:81]
	v_add_f32_e32 v118, v88, v118
	v_add_f32_e32 v118, v89, v118
	v_add_f32_e32 v118, v90, v118
	v_add_f32_e32 v118, v91, v118
	v_cvt_pk_bf16_f32 v152, v86, v87
	v_cvt_pk_bf16_f32 v153, v88, v89
	ds_read_b64_tr_b16 v[86:87], v220 offset:44032
	ds_read_b64_tr_b16 v[88:89], v220 offset:44544
	v_add_f32_e32 v118, v92, v118
	v_add_f32_e32 v118, v93, v118
	v_add_f32_e32 v118, v94, v118
	v_add_f32_e32 v118, v95, v118
	v_cvt_pk_bf16_f32 v146, v90, v91
	v_cvt_pk_bf16_f32 v147, v92, v93
	s_waitcnt lgkmcnt(14)
	v_mfma_f32_32x32x16_bf16 v[98:113], v[134:137], v[154:157], v[98:113]
	ds_read_b64_tr_b16 v[90:91], v220 offset:48128
	ds_read_b64_tr_b16 v[92:93], v220 offset:48640
	v_mfma_f32_32x32x16_bf16 v[66:81], v[130:133], v[154:157], v[66:81]
	v_add_f32_e32 v118, v96, v118
	v_add_f32_e32 v118, v97, v118
	v_add_f32_e32 v118, 0, v118
	v_cvt_pk_bf16_f32 v148, v94, v95
	v_cvt_pk_bf16_f32 v149, v96, v97
	v_lshl_add_u64 v[94:95], v[210:211], 0, s[52:53]
	s_mov_b32 s4, m0
	s_mov_b32 m0, s5
	s_nop 0
	global_load_lds_dwordx4 v[94:95], off
	s_mov_b32 m0, s4
	v_add_f32_e32 v118, v190, v118
	s_waitcnt lgkmcnt(14)
	v_mfma_f32_32x32x16_bf16 v[18:33], v[166:169], v[212:215], v[18:33]
	v_exp_f32_e32 v98, v98
	v_exp_f32_e32 v99, v99
	v_exp_f32_e32 v100, v100
	v_exp_f32_e32 v101, v101
	s_waitcnt lgkmcnt(12)
	v_mfma_f32_32x32x16_bf16 v[34:49], v[166:169], v[114:117], v[34:49]
	v_exp_f32_e32 v102, v102
	v_exp_f32_e32 v103, v103
	v_exp_f32_e32 v104, v104
	v_exp_f32_e32 v105, v105
	ds_read_b128 v[128:131], v219 offset:8192
	ds_read_b128 v[132:135], v219 offset:8704
	s_waitcnt lgkmcnt(12)
	v_mfma_f32_32x32x16_bf16 v[18:33], v[158:161], v[138:141], v[18:33]
	v_exp_f32_e32 v106, v106
	v_exp_f32_e32 v107, v107
	v_exp_f32_e32 v108, v108
	v_exp_f32_e32 v109, v109
	ds_read_b128 v[136:139], v219 offset:10240
	ds_read_b128 v[140:143], v219 offset:10752
	s_waitcnt lgkmcnt(12)
	v_mfma_f32_32x32x16_bf16 v[34:49], v[158:161], v[120:123], v[34:49]
	v_exp_f32_e32 v110, v110
	v_exp_f32_e32 v111, v111
	v_exp_f32_e32 v112, v112
	v_exp_f32_e32 v113, v113
	ds_read_b128 v[120:123], v219 offset:12288
	ds_read_b128 v[178:181], v219 offset:12800
	s_waitcnt lgkmcnt(12)
	v_mfma_f32_32x32x16_bf16 v[18:33], v[150:153], v[124:127], v[18:33]
	v_exp_f32_e32 v66, v66
	v_exp_f32_e32 v67, v67
	v_exp_f32_e32 v68, v68
	v_exp_f32_e32 v69, v69
	ds_read_b128 v[124:127], v219 offset:14336
	ds_read_b128 v[114:117], v219 offset:14848
	s_waitcnt lgkmcnt(12)
	v_mfma_f32_32x32x16_bf16 v[34:49], v[150:153], v[82:85], v[34:49]
	v_exp_f32_e32 v70, v70
	v_exp_f32_e32 v71, v71
	v_exp_f32_e32 v72, v72
	v_exp_f32_e32 v73, v73
	s_waitcnt lgkmcnt(10)
	v_mfma_f32_32x32x16_bf16 v[18:33], v[146:149], v[86:89], v[18:33]
	v_exp_f32_e32 v74, v74
	v_exp_f32_e32 v75, v75
	v_exp_f32_e32 v76, v76
	v_exp_f32_e32 v77, v77
	s_waitcnt lgkmcnt(8)
	v_mfma_f32_32x32x16_bf16 v[34:49], v[146:149], v[90:93], v[34:49]
	v_exp_f32_e32 v78, v78
	v_exp_f32_e32 v79, v79
	v_exp_f32_e32 v80, v80
	v_exp_f32_e32 v81, v81
	s_waitcnt vmcnt(0) lgkmcnt(0)
	s_barrier
; #define WAIT_BAR(N) asm volatile("s_waitcnt vmcnt(" #N ") lgkmcnt(0)\n\ts_barrier":::"memory")
;   #define RESC() do{}while(0)
;   #define ROT() do{sl_prev=sl_cur;sl_cur=sl_next;sl_next=(sl_next==(NSLOT-1)*SLOTB)?0:sl_next+SLOTB;}while(0)
;   #define ENDW(tt) do{ if((tt)+3<NT){WAIT_BAR(2);} else if((tt)+2<NT){WAIT_BAR(1);} else {WAIT_BAR(0);} }while(0)
; template<int THRL> __device__ __forceinline__ void attn_unit(int b,int h,int qb,const bf16*Q,const bf16*__restrict__ K,const bf16*__restrict__ V,bf16*O,char*shm,float m2){
;     ...
;   int t=1;
;   for(;t+5<NT;t+=2){
;     STEP(pB0,pB1,pA0,pA1,t,true,true,true);     WAIT_BAR(2); RESC(); ROT();
;     STEP(pA0,pA1,pB0,pB1,t+1,true,true,true);   WAIT_BAR(2); RESC(); ROT();
;   }
;     ...
;   for(;t+1<NT;t+=2){
;     STEP(pB0,pB1,pA0,pA1,t,(t+3<NT),(t+1<NT),(t+1<NT));       ENDW(t);   RESC(); ROT();
;     STEP(pA0,pA1,pB0,pB1,t+1,(t+4<NT),(t+2<NT),(t+2<NT));     ENDW(t+1); RESC(); ROT();
;   }
;   STEP(pB0,pB1,pA0,pA1,NT-1,false,false,false); RESC();
	ds_read_b64_tr_b16 v[182:183], v220 offset:24576
	ds_read_b64_tr_b16 v[184:185], v220 offset:25088
	v_add_f32_e32 v82, v98, v99
	v_add_f32_e32 v82, v100, v82
	v_add_f32_e32 v82, v101, v82
	v_add_f32_e32 v82, v102, v82
	v_add_f32_e32 v119, v103, v82
	v_cvt_pk_bf16_f32 v166, v98, v99
	v_cvt_pk_bf16_f32 v167, v100, v101
	s_waitcnt lgkmcnt(9)
	v_mfma_f32_32x32x16_bf16 v[82:97], v[128:131], v[174:177], v[50:65]
	ds_read_b64_tr_b16 v[98:99], v220 offset:28672
	ds_read_b64_tr_b16 v[100:101], v220 offset:29184
	s_waitcnt lgkmcnt(10)
	v_mfma_f32_32x32x16_bf16 v[50:65], v[132:135], v[174:177], v[50:65]
	v_add_f32_e32 v119, v104, v119
	v_add_f32_e32 v119, v105, v119
	v_add_f32_e32 v119, v106, v119
	v_add_f32_e32 v119, v107, v119
	v_cvt_pk_bf16_f32 v168, v102, v103
	v_cvt_pk_bf16_f32 v169, v104, v105
	ds_read_b64_tr_b16 v[102:103], v220 offset:25600
	ds_read_b64_tr_b16 v[104:105], v220 offset:26112
	v_add_f32_e32 v119, v108, v119
	v_add_f32_e32 v119, v109, v119
	v_add_f32_e32 v119, v110, v119
	v_add_f32_e32 v119, v111, v119
	v_cvt_pk_bf16_f32 v158, v106, v107
	v_cvt_pk_bf16_f32 v159, v108, v109
	s_waitcnt lgkmcnt(11)
	v_mfma_f32_32x32x16_bf16 v[82:97], v[136:139], v[170:173], v[82:97]
	ds_read_b64_tr_b16 v[106:107], v220 offset:29696
	ds_read_b64_tr_b16 v[108:109], v220 offset:30208
	s_waitcnt lgkmcnt(12)
	v_mfma_f32_32x32x16_bf16 v[50:65], v[140:143], v[170:173], v[50:65]
	v_add_f32_e32 v119, v112, v119
	v_add_f32_e32 v119, v113, v119
	v_add_f32_e32 v119, v66, v119
	v_add_f32_e32 v119, v67, v119
	v_cvt_pk_bf16_f32 v160, v110, v111
	v_cvt_pk_bf16_f32 v161, v112, v113
	ds_read_b64_tr_b16 v[110:111], v220 offset:26624
	ds_read_b64_tr_b16 v[112:113], v220 offset:27136
	v_add_f32_e32 v119, v68, v119
	v_add_f32_e32 v119, v69, v119
	v_add_f32_e32 v119, v70, v119
	v_add_f32_e32 v119, v71, v119
	v_cvt_pk_bf16_f32 v150, v66, v67
	v_cvt_pk_bf16_f32 v151, v68, v69
	s_waitcnt lgkmcnt(13)
	v_mfma_f32_32x32x16_bf16 v[82:97], v[120:123], v[162:165], v[82:97]
	ds_read_b64_tr_b16 v[66:67], v220 offset:30720
	ds_read_b64_tr_b16 v[68:69], v220 offset:31232
	s_waitcnt lgkmcnt(14)
	v_mfma_f32_32x32x16_bf16 v[50:65], v[178:181], v[162:165], v[50:65]
	v_add_f32_e32 v119, v72, v119
	v_add_f32_e32 v119, v73, v119
	v_add_f32_e32 v119, v74, v119
	v_add_f32_e32 v119, v75, v119
	v_cvt_pk_bf16_f32 v152, v70, v71
	v_cvt_pk_bf16_f32 v153, v72, v73
	ds_read_b64_tr_b16 v[70:71], v220 offset:27648
	ds_read_b64_tr_b16 v[72:73], v220 offset:28160
	v_add_f32_e32 v119, v76, v119
	v_add_f32_e32 v119, v77, v119
	v_add_f32_e32 v119, v78, v119
	v_add_f32_e32 v119, v79, v119
	v_cvt_pk_bf16_f32 v146, v74, v75
	v_cvt_pk_bf16_f32 v147, v76, v77
	s_waitcnt lgkmcnt(14)
	v_mfma_f32_32x32x16_bf16 v[82:97], v[124:127], v[154:157], v[82:97]
	ds_read_b64_tr_b16 v[74:75], v220 offset:31744
	ds_read_b64_tr_b16 v[76:77], v220 offset:32256
	v_mfma_f32_32x32x16_bf16 v[50:65], v[114:117], v[154:157], v[50:65]
	v_add_f32_e32 v114, v80, v119
	v_add_f32_e32 v114, v81, v114
	v_add_f32_e32 v114, 0, v114
	v_cvt_pk_bf16_f32 v148, v78, v79
	v_cvt_pk_bf16_f32 v149, v80, v81
	s_waitcnt lgkmcnt(14)
	v_mfma_f32_32x32x16_bf16 v[18:33], v[166:169], v[182:185], v[18:33]
	s_nop 1
	v_exp_f32_e32 v82, v82
	v_exp_f32_e32 v83, v83
	v_exp_f32_e32 v84, v84
	v_exp_f32_e32 v85, v85
	s_waitcnt lgkmcnt(12)
	v_mfma_f32_32x32x16_bf16 v[34:49], v[166:169], v[98:101], v[34:49]
	v_exp_f32_e32 v86, v86
	v_exp_f32_e32 v87, v87
	v_exp_f32_e32 v88, v88
	v_exp_f32_e32 v89, v89
	s_waitcnt lgkmcnt(10)
	v_mfma_f32_32x32x16_bf16 v[18:33], v[158:161], v[102:105], v[18:33]
	v_exp_f32_e32 v90, v90
	v_exp_f32_e32 v91, v91
	v_exp_f32_e32 v92, v92
	v_exp_f32_e32 v93, v93
	s_waitcnt lgkmcnt(8)
	v_mfma_f32_32x32x16_bf16 v[34:49], v[158:161], v[106:109], v[34:49]
	v_exp_f32_e32 v94, v94
	v_exp_f32_e32 v95, v95
	v_exp_f32_e32 v96, v96
	v_exp_f32_e32 v97, v97
	s_waitcnt lgkmcnt(6)
; #define SBAR() __builtin_amdgcn_sched_barrier(0)
;   #define PKW(P,B) cvtpk_s(P[B],P[B+1])
; template<int THRL> __device__ __forceinline__ void attn_unit(int b,int h,int qb,const bf16*Q,const bf16*__restrict__ K,const bf16*__restrict__ V,bf16*O,char*shm,float m2){
;     ...
;   { float sacc=pB0[0]+pB0[1]; _Pragma("unroll") for(int r=2;r<16;++r)sacc+=pB0[r]; _Pragma("unroll") for(int r=0;r<16;++r)sacc+=pB1[r]; l_reg+=sacc;
;     pw0=(u32x4){PKW(pB0,0),PKW(pB0,2),PKW(pB0,4),PKW(pB0,6)};pw1=(u32x4){PKW(pB0,8),PKW(pB0,10),PKW(pB0,12),PKW(pB0,14)};pw2=(u32x4){PKW(pB1,0),PKW(pB1,2),PKW(pB1,4),PKW(pB1,6)};pw3=(u32x4){PKW(pB1,8),PKW(pB1,10),PKW(pB1,12),PKW(pB1,14)};
;     SBAR(); pv(o,vb0+sl_cur,PAF(0),PAF(1),PAF(2),PAF(3)); }
;     ...
;   {auto rr=__builtin_amdgcn_permlane32_swap(__float_as_uint(l_reg),__float_as_uint(l_reg),false,false);l_reg=__uint_as_float(rr[0])+__uint_as_float(rr[1]);}
;   if(hi==0)wsf[32+r32]=l_reg;asm volatile("s_waitcnt lgkmcnt(0)":::"memory");
	v_mfma_f32_32x32x16_bf16 v[18:33], v[150:153], v[110:113], v[18:33]
	v_exp_f32_e32 v50, v50
	v_exp_f32_e32 v51, v51
	v_exp_f32_e32 v52, v52
	v_exp_f32_e32 v53, v53
	s_waitcnt lgkmcnt(4)
	v_mfma_f32_32x32x16_bf16 v[34:49], v[150:153], v[66:69], v[34:49]
	v_exp_f32_e32 v54, v54
	v_exp_f32_e32 v55, v55
	v_exp_f32_e32 v56, v56
	v_exp_f32_e32 v57, v57
	s_waitcnt lgkmcnt(2)
	v_mfma_f32_32x32x16_bf16 v[18:33], v[146:149], v[70:73], v[18:33]
	v_exp_f32_e32 v58, v58
	v_exp_f32_e32 v59, v59
	v_exp_f32_e32 v60, v60
	v_exp_f32_e32 v61, v61
	s_waitcnt lgkmcnt(0)
	v_mfma_f32_32x32x16_bf16 v[34:49], v[146:149], v[74:77], v[34:49]
	v_exp_f32_e32 v62, v62
	v_exp_f32_e32 v63, v63
	v_exp_f32_e32 v64, v64
	v_exp_f32_e32 v65, v65
	v_add_f32_e32 v66, v82, v83
	v_add_f32_e32 v66, v84, v66
	v_add_f32_e32 v66, v85, v66
	v_add_f32_e32 v66, v86, v66
	v_add_f32_e32 v66, v87, v66
	v_add_f32_e32 v66, v88, v66
	v_add_f32_e32 v66, v89, v66
	v_add_f32_e32 v66, v90, v66
	v_add_f32_e32 v66, v91, v66
	v_add_f32_e32 v66, v92, v66
	v_add_f32_e32 v66, v93, v66
	v_add_f32_e32 v66, v94, v66
	v_add_f32_e32 v66, v95, v66
	v_add_f32_e32 v66, v96, v66
	v_add_f32_e32 v66, v97, v66
	v_add_f32_e32 v66, v50, v66
	v_add_f32_e32 v66, v51, v66
	v_add_f32_e32 v66, v52, v66
	v_add_f32_e32 v66, v53, v66
	v_add_f32_e32 v66, v54, v66
	v_add_f32_e32 v66, v55, v66
	v_add_f32_e32 v66, v56, v66
	v_add_f32_e32 v66, v57, v66
	v_add_f32_e32 v66, v58, v66
	v_add_f32_e32 v66, v59, v66
	v_add_f32_e32 v66, v60, v66
	v_add_f32_e32 v66, v61, v66
	v_add_f32_e32 v66, v62, v66
	v_add_f32_e32 v66, v63, v66
	v_add_f32_e32 v66, v64, v66
	v_add_f32_e32 v66, v65, v66
	v_add_f32_e32 v67, v118, v114
	v_add_f32_e32 v66, v67, v66
	v_cvt_pk_bf16_f32 v50, v50, v51
	v_cvt_pk_bf16_f32 v68, v82, v83
	v_cvt_pk_bf16_f32 v69, v84, v85
	v_cvt_pk_bf16_f32 v70, v86, v87
	v_cvt_pk_bf16_f32 v71, v88, v89
	v_cvt_pk_bf16_f32 v72, v90, v91
	v_cvt_pk_bf16_f32 v73, v92, v93
	v_cvt_pk_bf16_f32 v74, v94, v95
	v_cvt_pk_bf16_f32 v75, v96, v97
	v_cvt_pk_bf16_f32 v51, v52, v53
	v_cvt_pk_bf16_f32 v52, v54, v55
	v_cvt_pk_bf16_f32 v53, v56, v57
	v_cvt_pk_bf16_f32 v54, v58, v59
	v_cvt_pk_bf16_f32 v55, v60, v61
	v_cvt_pk_bf16_f32 v56, v62, v63
	v_cvt_pk_bf16_f32 v57, v64, v65
	ds_read_b64_tr_b16 v[58:59],v221 offset:0
	ds_read_b64_tr_b16 v[60:61],v221 offset:512
	ds_read_b64_tr_b16 v[62:63],v221 offset:1024
	ds_read_b64_tr_b16 v[64:65],v221 offset:1536
	ds_read_b64_tr_b16 v[76:77],v221 offset:2048
	ds_read_b64_tr_b16 v[78:79],v221 offset:2560
	ds_read_b64_tr_b16 v[80:81],v221 offset:3072
	ds_read_b64_tr_b16 v[82:83],v221 offset:3584
	s_waitcnt lgkmcnt(0)
	s_nop 0
	v_mfma_f32_32x32x16_bf16 v[18:33], v[68:71], v[58:61], v[18:33]
	ds_read_b64_tr_b16 v[58:59],v221 offset:4096
	ds_read_b64_tr_b16 v[60:61],v221 offset:4608
	v_mfma_f32_32x32x16_bf16 v[18:33], v[72:75], v[62:65], v[18:33]
	ds_read_b64_tr_b16 v[62:63],v221 offset:5120
	ds_read_b64_tr_b16 v[64:65],v221 offset:5632
	v_mfma_f32_32x32x16_bf16 v[18:33], v[50:53], v[76:79], v[18:33]
	ds_read_b64_tr_b16 v[76:77],v221 offset:6144
	ds_read_b64_tr_b16 v[78:79],v221 offset:6656
	v_mfma_f32_32x32x16_bf16 v[18:33], v[54:57], v[80:83], v[18:33]
	ds_read_b64_tr_b16 v[80:81],v221 offset:7168
	ds_read_b64_tr_b16 v[82:83],v221 offset:7680
	s_waitcnt lgkmcnt(0)
	v_mfma_f32_32x32x16_bf16 v[34:49], v[68:71], v[58:61], v[34:49]
	v_mfma_f32_32x32x16_bf16 v[34:49], v[72:75], v[62:65], v[34:49]
	v_mfma_f32_32x32x16_bf16 v[34:49], v[50:53], v[76:79], v[34:49]
	v_mov_b32_e32 v50, v66
	s_nop 1
	v_permlane32_swap_b32_e32 v66, v50
	v_mfma_f32_32x32x16_bf16 v[34:49], v[54:57], v[80:83], v[34:49]
	s_and_saveexec_b64 s[4:5], s[2:3]
	s_cbranch_execz .LBB0_823
	v_add_f32_e32 v50, v66, v50
	v_lshl_add_u32 v51, v1, 2, s0
	ds_write_b32 v51, v50 offset:49280
	s_branch .LBB0_823
